# attention loop: early duplicate vmcnt(0) before each tile barrier replaced by s_nop (wait moved to first consumer), same code size
# speedup vs baseline: 1.0013x; 1.0013x over previous
; #define SBAR() __builtin_amdgcn_sched_barrier(0)
; #define TILE_SYNC() do { asm volatile("s_waitcnt vmcnt(0)" ::: "memory"); __syncthreads(); } while (0)
; #define RESC(a) do { if (__any((a) < 1.f)) { if (hi == 0) al_l[r32] = (a); asm volatile("s_waitcnt lgkmcnt(0)" ::: "memory"); \
;     _Pragma("unroll") for (int d = 0; d < 4; ++d) _Pragma("unroll") for (int r = 0; r < 16; ++r) o[d][r] *= al_l[crow(r, hi)]; } } while (0)
; __device__ __forceinline__ void attn_unit(const bf16_t* __restrict__ Qb, const bf16_t* __restrict__ Kh, const bf16_t* __restrict__ Vh, bf16_t* __restrict__ Ob, int seq, char* lds, LAS unsigned char* ldsl) {
;     ...
;     RESC(alB); TILE_SYNC();
;     sV = sK; sK = sN; sN = NEXT3(sN);
;     if (j + 2 < NT) KVDMA(j + 2, sN);
;     SBAR(); qkt(pA0, pA1, K_lds + sK * SHM_K, qr, qrl, qsw, r32, hi, -m_reg);
;     finishSM(pB0, pB1, alB, l_reg, pa0, pa1, pa2, pa3); SBAR();
;     pv_d0(o, vb0 + sV * SHM_V, pa0, pa1, pa2, pa3); partialSM(pA0, pA1, m_reg, alA, false);
;     RESC(alA); TILE_SYNC();
.LBB0_621:
	s_add_i32 s4, s44, 1
	s_nop 0
	s_cmp_lg_u32 s44, 2
	s_cselect_b32 s39, s4, 0
	s_add_i32 s4, s83, 1
	s_cmp_ge_u32 s4, s71
	s_waitcnt vmcnt(0)
	s_barrier
	s_cbranch_scc1 .LBB0_623
	s_mul_i32 s4, s39, 0x6000
	s_add_i32 s4, s19, s4
	v_lshl_add_u64 v[64:65], v[154:155], 0, s[24:25]
	s_add_i32 m0, s4, 0xc000
	s_nop 0
	global_load_lds_dwordx4 v[64:65], off
	v_lshl_add_u64 v[64:65], v[156:157], 0, s[24:25]
	s_add_i32 m0, s4, 0xc400
	s_nop 0
	global_load_lds_dwordx4 v[64:65], off
	s_add_i32 m0, s4, 0xc800
	s_lshl_b32 s4, s39, 14
	v_lshl_add_u64 v[64:65], v[158:159], 0, s[24:25]
	s_add_i32 s10, s82, s4
	s_mov_b64 s[4:5], 0x2a024800
	global_load_lds_dwordx4 v[64:65], off
	v_lshl_add_u64 v[64:65], v[152:153], 0, s[4:5]
	s_mov_b32 m0, s10
	s_mov_b64 s[4:5], 0x2a024880
	global_load_lds_dwordx4 v[64:65], off
	v_lshl_add_u64 v[64:65], v[152:153], 0, s[4:5]
	s_add_i32 m0, s10, 0x400
	s_nop 0
	global_load_lds_dwordx4 v[64:65], off

; #define TILE_SYNC() do { asm volatile("s_waitcnt vmcnt(0)" ::: "memory"); __syncthreads(); } while (0)
; #define RESC(a) do { if (__any((a) < 1.f)) { if (hi == 0) al_l[r32] = (a); asm volatile("s_waitcnt lgkmcnt(0)" ::: "memory"); \
;     _Pragma("unroll") for (int d = 0; d < 4; ++d) _Pragma("unroll") for (int r = 0; r < 16; ++r) o[d][r] *= al_l[crow(r, hi)]; } } while (0)
; __device__ __forceinline__ void finishSM(f32x16& p0, f32x16& p1, float alpha, float& l_reg, bf16x8& pa0, bf16x8& pa1, bf16x8& pa2, bf16x8& pa3) {
; #pragma unroll
;   for (int r = 0; r < 16; ++r) p1[r] = __builtin_amdgcn_exp2f(p1[r]);
;   float ps = 0;
; #pragma unroll
;   for (int r = 0; r < 16; ++r) ps += p0[r];
; #pragma unroll
;   for (int r = 0; r < 16; ++r) ps += p1[r];
;   { auto rr = __builtin_amdgcn_permlane32_swap(__float_as_uint(ps), __float_as_uint(ps), false, false);
;     ps = __uint_as_float(rr[0]) + __uint_as_float(rr[1]); }
;   l_reg = l_reg * alpha + ps;
; __device__ __forceinline__ void attn_unit(const bf16_t* __restrict__ Qb, const bf16_t* __restrict__ Kh, const bf16_t* __restrict__ Vh, bf16_t* __restrict__ Ob, int seq, char* lds, LAS unsigned char* ldsl) {
;     ...
;     RESC(alA); TILE_SYNC();
;     sV = sK; sK = sN; sN = NEXT3(sN);
;   }
.LBB0_628:
	v_exp_f32_e32 v211, v96
	v_exp_f32_e32 v214, v97
	v_exp_f32_e32 v212, v98
	v_exp_f32_e32 v215, v99
	v_exp_f32_e32 v213, v100
	v_exp_f32_e32 v216, v101
	v_exp_f32_e32 v209, v102
	v_exp_f32_e32 v210, v103
	v_exp_f32_e32 v205, v104
	v_exp_f32_e32 v207, v105
	v_exp_f32_e32 v206, v106
	v_exp_f32_e32 v208, v107
	v_exp_f32_e32 v186, v108
	v_exp_f32_e32 v195, v109
	v_exp_f32_e32 v187, v110
	v_exp_f32_e32 v204, v111
	s_add_i32 s4, s39, 1
	v_add_f32_e32 v82, v183, v184
	s_nop 0
	s_cmp_lg_u32 s39, 2
	v_fmac_f32_e32 v82, v182, v163
	v_add_f32_e32 v163, v80, v81
	s_cselect_b32 s5, s4, 0
	s_add_i32 s83, s83, 2
	v_fmac_f32_e32 v163, v82, v185
	v_lshl_add_u64 v[144:145], v[144:145], 0, s[72:73]
	v_lshl_add_u64 v[146:147], v[146:147], 0, s[26:27]
	v_lshl_add_u64 v[148:149], v[148:149], 0, s[26:27]
	s_cmp_ge_u32 s83, s71
	v_lshl_add_u64 v[150:151], v[150:151], 0, s[26:27]
	s_waitcnt vmcnt(0)
	s_barrier
	s_cbranch_scc1 .LBB0_632
	s_mov_b32 s84, s39
	v_mov_b32_e32 v182, v152
	s_branch .LBB0_616
